# attention K/V staging: counted vmcnt so tile loads stay in flight two steps; q-fragment wait hoisted before the tile loop
# baseline (speedup 1.0000x reference)
; #define LAS __attribute__((address_space(3)))
; #define LDS_BARRIER() asm volatile("s_waitcnt lgkmcnt(0)\n\ts_barrier" ::: "memory")
; #define AT_LOAD(K_, V_, kt) do { const bf16_t* s_ = kvsrc + (size_t)(kt) * 64 * NQKV; K_ = *(const bf16x8*)s_; V_ = *(const bf16x8*)(s_ + 1024); } while (0)
; #define AT_STORE(K_, V_, buf) do { *(LAS bf16x8*)(lds + AT_KOFF + (buf) * 9216 + srow * 144 + sch * 16) = K_; \
;         _Pragma("unroll") for (int j_ = 0; j_ < 8; ++j_) *(LAS short*)(lds + AT_VOFF + (buf) * 9216 + (8 * sch + j_) * 144 + vp * 2) = V_[j_]; } while (0)
; __device__ __forceinline__ void attn_prompt_unit(const Params& P, LAS unsigned char* lds, int li, int b, int h, int g4, const int tid) {
;     ...
;     const size_t qrow = (size_t)b * SEQ + 256 * g4 + 32 * wid + r32;
;     bf16x8 qr[4];
; #pragma unroll
;     for (int d0 = 0; d0 < 4; ++d0) qr[d0] = *(const bf16x8*)(QKV + qrow * NQKV + h * 64 + d0 * 16 + hi * 8);
;     const int kt_lo = max(0, 4 * g4 - 8), kt_hi = 4 * g4 + 3;
;     const int srow = tid & 63, sch = tid >> 6;
;     const bf16_t* kvsrc = QKV + ((size_t)b * SEQ + srow) * NQKV + 1024 + h * 64 + 8 * sch;
;     const int vp = vpos(srow);
;     bf16x8 kA, vA, kB, vB;
;     ...
;     AT_LOAD(kA, vA, kt_lo); AT_LOAD(kB, vB, kt_lo + 1);
;     AT_STORE(kA, vA, 0);
;     LDS_BARRIER();
;     float m = -1e30f, l = 0.f; f32x16 o[2];
; #pragma unroll
;     for (int r = 0; r < 16; ++r) { o[0][r] = 0.f; o[1][r] = 0.f; }
;     const LAS f32x4* btl = (const LAS f32x4*)(lds + AT_BIAS) + (wid & 1) * 512 + lane;
.LBB0_69:
	s_ashr_i32 s0, s2, 8
	s_and_b32 s15, s2, 15
	v_readfirstlane_b32 s18, v110
	s_ashr_i32 s1, s0, 31
	s_lshl_b64 s[22:23], s[0:1], 12
	s_lshl_b32 s26, s18, 5
	v_lshl_or_b32 v0, s15, 8, v109
	s_ashr_i32 s27, s26, 31
	v_or_b32_e32 v0, s22, v0
	v_mov_b32_e32 v1, s23
	v_lshl_add_u64 v[104:105], v[0:1], 0, s[26:27]
	v_mov_b64_e32 v[0:1], s[64:65]
	s_lshl_b32 s1, s2, 2
	v_or_b32_e32 v4, s22, v164
	v_mad_u64_u32 v[2:3], s[26:27], v104, s66, v[0:1]
	s_and_b32 s1, s1, 0x3c0
	v_mad_u64_u32 v[0:1], s[26:27], v4, s66, v[0:1]
	s_lshl_b32 s36, s1, 1
	v_mad_i32_i24 v1, s23, v198, v1
	s_lshl_b32 s15, s15, 2
	v_lshl_add_u64 v[0:1], v[0:1], 0, s[36:37]
	v_sub_u32_e64 v16, s15, 8 clamp
	v_lshl_add_u64 v[0:1], v[96:97], 1, v[0:1]
	s_mov_b32 s1, 0x60000
	v_mad_i32_i24 v3, v105, s66, v3
	v_mad_u64_u32 v[4:5], s[22:23], v16, s1, v[0:1]
	s_mov_b64 s[26:27], 0x800
	v_lshl_add_u64 v[2:3], v[2:3], 0, s[36:37]
	v_lshl_add_u64 v[6:7], v[4:5], 0, s[26:27]
	global_load_dwordx4 v[76:79], v[4:5], off offset:2048
	global_load_dwordx4 v[84:87], v[6:7], off offset:2048
	v_mov_b32_e32 v101, v161
	v_lshl_add_u64 v[2:3], v[2:3], 0, v[100:101]
	s_max_u32 s1, s15, 8
	global_load_dwordx4 v[64:67], v[2:3], off
	global_load_dwordx4 v[68:71], v[2:3], off offset:32
	global_load_dwordx4 v[72:75], v[2:3], off offset:64
	global_load_dwordx4 v[80:83], v[2:3], off offset:96
	s_add_i32 s1, s1, -7
	v_mad_u64_u32 v[0:1], s[22:23], s1, v199, v[0:1]
	v_lshl_add_u64 v[2:3], v[0:1], 0, s[26:27]
	global_load_dwordx4 v[88:91], v[0:1], off offset:2048
	global_load_dwordx4 v[92:95], v[2:3], off offset:2048
	s_or_b32 s17, s15, 3
	v_mov_b32_e32 v15, 0
	v_cmp_lt_u32_e32 vcc, s17, v16
	v_mov_b32_e32 v14, v15
	v_mov_b32_e32 v13, v15
	v_mov_b32_e32 v12, v15
	s_waitcnt vmcnt(8)
	v_mov_b32_e32 v11, v15
	v_mov_b32_e32 v10, v15
	v_mov_b32_e32 v9, v15
	v_mov_b32_e32 v8, v15
	v_mov_b32_e32 v7, v15
	v_mov_b32_e32 v6, v15
	v_mov_b32_e32 v5, v15
	v_mov_b32_e32 v4, v15
	v_mov_b32_e32 v3, v15
	v_mov_b32_e32 v2, v15
	v_mov_b32_e32 v1, v15
	v_mov_b32_e32 v0, v15
	v_mov_b32_e32 v31, v15
	v_mov_b32_e32 v30, v15
	v_mov_b32_e32 v29, v15
	v_mov_b32_e32 v28, v15
	v_mov_b32_e32 v27, v15
	v_mov_b32_e32 v26, v15
	v_mov_b32_e32 v25, v15
	v_mov_b32_e32 v24, v15
	v_mov_b32_e32 v23, v15
	v_mov_b32_e32 v22, v15
	v_mov_b32_e32 v21, v15
	v_mov_b32_e32 v20, v15
	v_mov_b32_e32 v19, v15
	v_readfirstlane_b32 s28, v16
	s_and_b64 vcc, exec, vcc
	v_mov_b32_e32 v18, v15
	v_mov_b32_e32 v17, v15
	v_mov_b32_e32 v16, v15
	v_mov_b32_e32 v101, v15
	s_waitcnt vmcnt(7)
	ds_write_b128 v114, v[76:79]
	s_waitcnt vmcnt(2)
	ds_write_b16 v115, v84 offset:18432
	ds_write_b16_d16_hi v115, v84 offset:18576
	ds_write_b16 v115, v85 offset:18720
	ds_write_b16_d16_hi v115, v85 offset:18864
	ds_write_b16 v115, v86 offset:19008
	ds_write_b16_d16_hi v115, v86 offset:19152
	ds_write_b16 v115, v87 offset:19296
	ds_write_b16_d16_hi v115, v87 offset:19440
	s_waitcnt lgkmcnt(0)
	s_barrier
	s_cbranch_vccnz .LBB0_68
	s_ashr_i32 s26, s18, 1
	s_lshl_b32 s18, s18, 13
	s_max_u32 s1, s13, 8
	s_lshl_b32 s19, s12, 1
	s_and_b32 s18, s18, 0x2000
	s_sub_i32 s22, 0, s1
	s_and_b32 s19, s19, 0x780
	s_mul_i32 s1, s1, 0x60000
	s_add_i32 s23, s26, s15
	v_add_u32_e32 v103, s18, v111
	s_mul_hi_i32 s18, s0, 0x1800000
	s_mul_i32 s0, s0, 0x1800000
	s_add_i32 s1, s1, 0xffd00000
	s_add_i32 s25, s23, -8
	s_add_i32 s26, s26, s14
	s_or_b32 s0, s0, s19
	s_add_u32 s0, s0, s1
	s_addc_u32 s1, s18, 0
	v_mov_b32_e32 v101, 0
	v_lshl_add_u64 v[106:107], v[98:99], 0, s[0:1]
	v_mov_b32_e32 v117, 0xf149f2ca
	v_mov_b32_e32 v16, 0
	v_mov_b32_e32 v17, v101
	v_mov_b32_e32 v18, v101
	v_mov_b32_e32 v19, v101
	v_mov_b32_e32 v20, v101
	v_mov_b32_e32 v21, v101
	v_mov_b32_e32 v22, v101
	v_mov_b32_e32 v23, v101
	v_mov_b32_e32 v24, v101
	v_mov_b32_e32 v25, v101
	v_mov_b32_e32 v26, v101
	v_mov_b32_e32 v27, v101
	v_mov_b32_e32 v28, v101
	v_mov_b32_e32 v29, v101
	v_mov_b32_e32 v30, v101
	v_mov_b32_e32 v31, v101
	v_mov_b32_e32 v0, v101
	v_mov_b32_e32 v1, v101
	v_mov_b32_e32 v2, v101
	v_mov_b32_e32 v3, v101
	v_mov_b32_e32 v4, v101
	v_mov_b32_e32 v5, v101
	v_mov_b32_e32 v6, v101
	v_mov_b32_e32 v7, v101
	v_mov_b32_e32 v8, v101
	v_mov_b32_e32 v9, v101
	v_mov_b32_e32 v10, v101
	v_mov_b32_e32 v11, v101
	v_mov_b32_e32 v12, v101
	v_mov_b32_e32 v13, v101
	v_mov_b32_e32 v14, v101
	v_mov_b32_e32 v15, v101

; #define LAS __attribute__((address_space(3)))
; __device__ __forceinline__ void attn_tile(const LAS unsigned char* Kb, const LAS unsigned char* Vb, const LAS f32x4* bp, const bf16x8 (&qr)[4], f32x16 (&o)[2], float& m, float& l, int r32, int hi) {
;     const float C2 = 0.125f * LOG2E;
;     f32x16 p0, p1;
; #pragma unroll
;     for (int j = 0; j < 4; ++j) { const f32x4 t0 = bp[j * 64], t1 = bp[(4 + j) * 64];
;         p0[4 * j] = t0[0]; p0[4 * j + 1] = t0[1]; p0[4 * j + 2] = t0[2]; p0[4 * j + 3] = t0[3]; p1[4 * j] = t1[0]; p1[4 * j + 1] = t1[1]; p1[4 * j + 2] = t1[2]; p1[4 * j + 3] = t1[3]; }
; #pragma unroll
;     for (int d0 = 0; d0 < 4; ++d0) {
;         const bf16x8 a0 = *(const LAS bf16x8*)(Kb + r32 * 144 + d0 * 32 + hi * 16);
;         const bf16x8 a1 = *(const LAS bf16x8*)(Kb + (32 + r32) * 144 + d0 * 32 + hi * 16);
;         p0 = __builtin_amdgcn_mfma_f32_32x32x16_bf16(a0, qr[d0], p0, 0, 0, 0);
;         p1 = __builtin_amdgcn_mfma_f32_32x32x16_bf16(a1, qr[d0], p1, 0, 0, 0);
;     }
;     float mx = fmaxf(p0[0], p1[0]);
; #pragma unroll
;     for (int r = 1; r < 16; ++r) mx = fmaxf(mx, fmaxf(p0[r], p1[r]));
;     mx = fmaxf(mx, __shfl_xor(mx, 32)) * C2;
;     if (__any(mx > m + 8.0f)) {
;         const float mn = fmaxf(m, mx), scl = __builtin_amdgcn_exp2f(m - mn); m = mn; l *= scl;
; #pragma unroll
;         for (int r = 0; r < 16; ++r) { o[0][r] *= scl; o[1][r] *= scl; }
;     }
.LBB0_73:
	s_cmp_lt_i32 s28, s25
	s_cselect_b64 s[30:31], -1, 0
	s_cmp_gt_i32 s28, s23
	s_cselect_b64 s[34:35], -1, 0
	s_or_b64 s[30:31], s[30:31], s[34:35]
	s_and_b64 vcc, exec, s[30:31]
	s_cbranch_vccnz .LBB0_77
	s_add_i32 s29, s22, s26
	s_add_i32 s29, s29, 1
	s_min_i32 s29, s29, 3
	v_lshl_add_u32 v158, s29, 14, v103
	ds_read_b128 v[48:51], v158 offset:36864
	ds_read_b128 v[52:55], v158 offset:37888
	ds_read_b128 v[56:59], v158 offset:38912
	ds_read_b128 v[60:63], v158 offset:39936
	ds_read_b128 v[138:141], v116 offset:0
	ds_read_b128 v[142:145], v116 offset:4608
	ds_read_b128 v[32:35], v158 offset:40960
	ds_read_b128 v[36:39], v158 offset:41984
	ds_read_b128 v[40:43], v158 offset:43008
	ds_read_b128 v[44:47], v158 offset:44032
	ds_read_b128 v[146:149], v116 offset:32
	ds_read_b128 v[150:153], v116 offset:4640
	ds_read_b128 v[154:157], v116 offset:64
	ds_read_b128 v[118:121], v116 offset:4672
	ds_read_b128 v[122:125], v116 offset:96
	v_add_u32_e32 v133, v113, v112
	v_xor_b32_e32 v132, 32, v200
	s_waitcnt lgkmcnt(10)
	v_mfma_f32_32x32x16_bf16 v[48:63], v[138:141], v[64:67], v[48:63]
	ds_read_b128 v[126:129], v116 offset:4704
	s_waitcnt lgkmcnt(6)
	v_mfma_f32_32x32x16_bf16 v[32:47], v[142:145], v[64:67], v[32:47]
	v_lshlrev_b32_e32 v132, 2, v132
	s_waitcnt lgkmcnt(5)
	v_mfma_f32_32x32x16_bf16 v[48:63], v[146:149], v[68:71], v[48:63]
	s_waitcnt lgkmcnt(4)
	v_mfma_f32_32x32x16_bf16 v[32:47], v[150:153], v[68:71], v[32:47]
	s_waitcnt lgkmcnt(3)
	v_mfma_f32_32x32x16_bf16 v[48:63], v[154:157], v[72:75], v[48:63]
	s_waitcnt lgkmcnt(2)
	v_mfma_f32_32x32x16_bf16 v[32:47], v[118:121], v[72:75], v[32:47]
	s_waitcnt lgkmcnt(1)
	v_mfma_f32_32x32x16_bf16 v[48:63], v[122:125], v[80:83], v[48:63]
	s_waitcnt lgkmcnt(0)
	v_mfma_f32_32x32x16_bf16 v[32:47], v[126:129], v[80:83], v[32:47]
	ds_read_b128 v[138:141], v133 offset:18432
	ds_read_b128 v[142:145], v133 offset:18464
	ds_read_b128 v[146:149], v133 offset:18496
	ds_read_b128 v[150:153], v133 offset:18528
	ds_read_b128 v[154:157], v133 offset:23040
	ds_read_b128 v[118:121], v133 offset:23072
	ds_read_b128 v[122:125], v133 offset:23104
	ds_read_b128 v[126:129], v133 offset:23136
	v_add_f32_e32 v159, 0x41000000, v117
	s_nop 1
	v_max3_f32 v130, v48, v49, v50
	v_max3_f32 v130, v130, v51, v52
	v_max3_f32 v130, v130, v53, v54
	v_max3_f32 v131, v32, v33, v34
	v_max3_f32 v130, v130, v55, v56
	v_max3_f32 v131, v131, v35, v36
	v_max3_f32 v130, v130, v57, v58
	v_max3_f32 v131, v131, v37, v38
	v_max3_f32 v130, v130, v59, v60
	v_max3_f32 v131, v131, v39, v40
	v_max3_f32 v130, v130, v61, v62
	v_max3_f32 v131, v131, v41, v42
	v_max_f32_e32 v130, v130, v63
	v_max3_f32 v131, v131, v43, v44
	v_max3_f32 v131, v131, v45, v46
	v_max_f32_e32 v131, v131, v47
	v_max_f32_e32 v130, v130, v131
	ds_bpermute_b32 v131, v132, v130
	s_waitcnt lgkmcnt(0)
	v_max_f32_e32 v130, v130, v131
	v_mul_f32_e32 v130, 0x3e38aa3b, v130
	v_cmp_gt_f32_e32 vcc, v130, v159
	s_cbranch_vccz .Latt_keep_a
	v_max_f32_e32 v131, v117, v130
	v_sub_f32_e32 v117, v117, v131
	v_exp_f32_e32 v130, v117
	v_mov_b32_e32 v117, v131
	v_mul_f32_e32 v101, v101, v130
	v_pk_mul_f32 v[0:1], v[0:1], v[130:131] op_sel_hi:[1,0]
	v_pk_mul_f32 v[2:3], v[2:3], v[130:131] op_sel_hi:[1,0]
	v_pk_mul_f32 v[4:5], v[4:5], v[130:131] op_sel_hi:[1,0]
	v_pk_mul_f32 v[6:7], v[6:7], v[130:131] op_sel_hi:[1,0]
	v_pk_mul_f32 v[8:9], v[8:9], v[130:131] op_sel_hi:[1,0]
	v_pk_mul_f32 v[10:11], v[10:11], v[130:131] op_sel_hi:[1,0]
	v_pk_mul_f32 v[12:13], v[12:13], v[130:131] op_sel_hi:[1,0]
	v_pk_mul_f32 v[14:15], v[14:15], v[130:131] op_sel_hi:[1,0]
	v_pk_mul_f32 v[16:17], v[16:17], v[130:131] op_sel_hi:[1,0]
	v_pk_mul_f32 v[18:19], v[18:19], v[130:131] op_sel_hi:[1,0]
	v_pk_mul_f32 v[20:21], v[20:21], v[130:131] op_sel_hi:[1,0]
	v_pk_mul_f32 v[22:23], v[22:23], v[130:131] op_sel_hi:[1,0]
	v_pk_mul_f32 v[24:25], v[24:25], v[130:131] op_sel_hi:[1,0]
	v_pk_mul_f32 v[26:27], v[26:27], v[130:131] op_sel_hi:[1,0]
	v_pk_mul_f32 v[28:29], v[28:29], v[130:131] op_sel_hi:[1,0]
	v_pk_mul_f32 v[30:31], v[30:31], v[130:131] op_sel_hi:[1,0]

; #define AT_STORE(K_, V_, buf) do { *(LAS bf16x8*)(lds + AT_KOFF + (buf) * 9216 + srow * 144 + sch * 16) = K_; \
;         _Pragma("unroll") for (int j_ = 0; j_ < 8; ++j_) *(LAS short*)(lds + AT_VOFF + (buf) * 9216 + (8 * sch + j_) * 144 + vp * 2) = V_[j_]; } while (0)
; __device__ __forceinline__ void attn_prompt_unit(const Params& P, LAS unsigned char* lds, int li, int b, int h, int g4, const int tid) {
;     ...
;         if (kt >= cw - 8 && kt <= cw) attn_tile(lds + AT_KOFF, lds + AT_VOFF, btl + min(cw - kt, 3) * 1024, qr, o, m, l, r32, hi);
;         AT_STORE(kB, vB, 1);
.LBB0_77:
	s_and_b64 vcc, exec, s[18:19]
	s_cbranch_vccz .Latt_b0
	s_waitcnt vmcnt(2)
	s_branch .Latt_b1

; #define LAS __attribute__((address_space(3)))
; #define LDS_BARRIER() asm volatile("s_waitcnt lgkmcnt(0)\n\ts_barrier" ::: "memory")
; #define AT_LOAD(K_, V_, kt) do { const bf16_t* s_ = kvsrc + (size_t)(kt) * 64 * NQKV; K_ = *(const bf16x8*)s_; V_ = *(const bf16x8*)(s_ + 1024); } while (0)
; #define AT_STORE(K_, V_, buf) do { *(LAS bf16x8*)(lds + AT_KOFF + (buf) * 9216 + srow * 144 + sch * 16) = K_; \
;         _Pragma("unroll") for (int j_ = 0; j_ < 8; ++j_) *(LAS short*)(lds + AT_VOFF + (buf) * 9216 + (8 * sch + j_) * 144 + vp * 2) = V_[j_]; } while (0)
; __device__ __forceinline__ void attn_prompt_unit(const Params& P, LAS unsigned char* lds, int li, int b, int h, int g4, const int tid) {
;     ...
;     AT_LOAD(kA, vA, kt_lo); AT_LOAD(kB, vB, kt_lo + 1);
;     AT_STORE(kA, vA, 0);
;     LDS_BARRIER();
;     float m = -1e30f, l = 0.f; f32x16 o[2];
; #pragma unroll
;     for (int r = 0; r < 16; ++r) { o[0][r] = 0.f; o[1][r] = 0.f; }
;     const LAS f32x4* btl = (const LAS f32x4*)(lds + AT_BIAS) + (wid & 1) * 512 + lane;
;     for (int kt = kt_lo; kt <= kt_hi; kt += 2) {
;         if (kt + 2 <= kt_hi) AT_LOAD(kA, vA, kt + 2);
;         if (kt >= cw - 8 && kt <= cw) attn_tile(lds + AT_KOFF, lds + AT_VOFF, btl + min(cw - kt, 3) * 1024, qr, o, m, l, r32, hi);
;         AT_STORE(kB, vB, 1);
;         LDS_BARRIER();
;         if (kt + 3 <= kt_hi) AT_LOAD(kB, vB, kt + 3);
.Latt_b1:
	ds_write_b128 v114, v[88:91] offset:9216
	ds_write_b16 v115, v92 offset:27648
	ds_write_b16_d16_hi v115, v92 offset:27792
	ds_write_b16 v115, v93 offset:27936
	ds_write_b16_d16_hi v115, v93 offset:28080
	ds_write_b16 v115, v94 offset:28224
	ds_write_b16_d16_hi v115, v94 offset:28368
	ds_write_b16 v115, v95 offset:28512
	ds_write_b16_d16_hi v115, v95 offset:28656
	s_waitcnt lgkmcnt(0)
	s_barrier
	s_cmp_gt_u32 s28, s15
	s_cselect_b32 s34, 0, 2
	s_cbranch_scc1 .LBB0_79
	global_load_dwordx4 v[88:91], v[106:107], off offset:-2048
	global_load_dwordx4 v[92:95], v[106:107], off

; #define AT_LOAD(K_, V_, kt) do { const bf16_t* s_ = kvsrc + (size_t)(kt) * 64 * NQKV; K_ = *(const bf16x8*)s_; V_ = *(const bf16x8*)(s_ + 1024); } while (0)
; #define AT_STORE(K_, V_, buf) do { *(LAS bf16x8*)(lds + AT_KOFF + (buf) * 9216 + srow * 144 + sch * 16) = K_; \
;         _Pragma("unroll") for (int j_ = 0; j_ < 8; ++j_) *(LAS short*)(lds + AT_VOFF + (buf) * 9216 + (8 * sch + j_) * 144 + vp * 2) = V_[j_]; } while (0)
; __device__ __forceinline__ void attn_prompt_unit(const Params& P, LAS unsigned char* lds, int li, int b, int h, int g4, const int tid) {
;     ...
;         if (kt + 3 <= kt_hi) AT_LOAD(kB, vB, kt + 3);
;         if (kt + 1 >= cw - 8 && kt + 1 <= cw) attn_tile(lds + AT_KOFF + 9216, lds + AT_VOFF + 9216, btl + min(cw - kt - 1, 3) * 1024, qr, o, m, l, r32, hi);
;         if (kt + 2 <= kt_hi) AT_STORE(kA, vA, 0);
.LBB0_83:
	s_andn2_b64 vcc, exec, s[18:19]
	s_cbranch_vccnz .LBB0_85
	s_cmp_eq_u32 s34, 0
	s_cbranch_scc1 .Latt_a0
	s_waitcnt vmcnt(2)
	s_branch .Latt_a1

; #define AT_STORE(K_, V_, buf) do { *(LAS bf16x8*)(lds + AT_KOFF + (buf) * 9216 + srow * 144 + sch * 16) = K_; \
;         _Pragma("unroll") for (int j_ = 0; j_ < 8; ++j_) *(LAS short*)(lds + AT_VOFF + (buf) * 9216 + (8 * sch + j_) * 144 + vp * 2) = V_[j_]; } while (0)
; __device__ __forceinline__ void attn_prompt_unit(const Params& P, LAS unsigned char* lds, int li, int b, int h, int g4, const int tid) {
;     ...
;         if (kt + 2 <= kt_hi) AT_STORE(kA, vA, 0);
.Latt_a1:
	ds_write_b128 v114, v[76:79]
	ds_write_b16 v115, v84 offset:18432
	ds_write_b16_d16_hi v115, v84 offset:18576
	ds_write_b16 v115, v85 offset:18720
	ds_write_b16_d16_hi v115, v85 offset:18864
	ds_write_b16 v115, v86 offset:19008
	ds_write_b16_d16_hi v115, v86 offset:19152
	ds_write_b16 v115, v87 offset:19296
	ds_write_b16_d16_hi v115, v87 offset:19440
